# sc1 stores also for next-layer weight conversion in up-phase tail
# baseline (speedup 1.0000x reference)
.LBB0_793:
	v_add_u32_e32 v66, s30, v4
	v_ashrrev_i32_e32 v67, 31, v66
	v_lshlrev_b64 v[66:67], 11, v[66:67]
	v_lshl_add_u64 v[66:67], s[42:43], 0, v[66:67]
	v_lshl_add_u64 v[66:67], s[28:29], 1, v[66:67]
	s_waitcnt vmcnt(62)
	v_cvt_pk_bf16_f32 v0, v0, v1
	s_waitcnt vmcnt(60)
	v_cvt_pk_bf16_f32 v1, v2, v3
	s_waitcnt vmcnt(58)
	v_cvt_pk_bf16_f32 v2, v6, v7
	s_waitcnt vmcnt(56)
	v_cvt_pk_bf16_f32 v3, v8, v9
	global_store_dwordx4 v[66:67], v[0:3], off sc1
	s_waitcnt vmcnt(55)
	s_nop 0
	v_cvt_pk_bf16_f32 v0, v10, v11
	s_waitcnt vmcnt(53)
	v_cvt_pk_bf16_f32 v1, v12, v13
	s_waitcnt vmcnt(51)
	v_cvt_pk_bf16_f32 v2, v14, v15
	s_waitcnt vmcnt(49)
	v_cvt_pk_bf16_f32 v3, v16, v17
	global_store_dwordx4 v[66:67], v[0:3], off offset:16 sc1
	s_waitcnt vmcnt(48)
	s_nop 0
	v_cvt_pk_bf16_f32 v0, v18, v19
	s_waitcnt vmcnt(46)
	v_cvt_pk_bf16_f32 v1, v20, v21
	s_waitcnt vmcnt(44)
	v_cvt_pk_bf16_f32 v2, v22, v23
	s_waitcnt vmcnt(42)
	v_cvt_pk_bf16_f32 v3, v24, v25
	global_store_dwordx4 v[66:67], v[0:3], off offset:32 sc1
	s_waitcnt vmcnt(41)
	s_nop 0
	v_cvt_pk_bf16_f32 v0, v26, v27
	s_waitcnt vmcnt(39)
	v_cvt_pk_bf16_f32 v1, v28, v29
	s_waitcnt vmcnt(37)
	v_cvt_pk_bf16_f32 v2, v30, v31
	s_waitcnt vmcnt(35)
	v_cvt_pk_bf16_f32 v3, v32, v33
	global_store_dwordx4 v[66:67], v[0:3], off offset:48 sc1
	s_waitcnt vmcnt(34)
	s_nop 0
	v_cvt_pk_bf16_f32 v0, v34, v35
	s_waitcnt vmcnt(32)
	v_cvt_pk_bf16_f32 v1, v36, v37
	s_waitcnt vmcnt(30)
	v_cvt_pk_bf16_f32 v2, v38, v39
	s_waitcnt vmcnt(28)
	v_cvt_pk_bf16_f32 v3, v40, v41
	global_store_dwordx4 v[66:67], v[0:3], off offset:64 sc1
	s_waitcnt vmcnt(27)
	s_nop 0
	v_cvt_pk_bf16_f32 v0, v42, v43
	s_waitcnt vmcnt(25)
	v_cvt_pk_bf16_f32 v1, v44, v45
	s_waitcnt vmcnt(23)
	v_cvt_pk_bf16_f32 v2, v46, v47
	s_waitcnt vmcnt(21)
	v_cvt_pk_bf16_f32 v3, v48, v49
	global_store_dwordx4 v[66:67], v[0:3], off offset:80 sc1
	s_waitcnt vmcnt(20)
	s_nop 0
	v_cvt_pk_bf16_f32 v0, v50, v51
	s_waitcnt vmcnt(18)
	v_cvt_pk_bf16_f32 v1, v52, v53
	s_waitcnt vmcnt(16)
	v_cvt_pk_bf16_f32 v2, v54, v55
	s_waitcnt vmcnt(14)
	v_cvt_pk_bf16_f32 v3, v56, v57
	global_store_dwordx4 v[66:67], v[0:3], off offset:96 sc1
	s_waitcnt vmcnt(13)
	s_nop 0
	v_cvt_pk_bf16_f32 v0, v58, v59
	s_waitcnt vmcnt(11)
	v_cvt_pk_bf16_f32 v1, v60, v61
	s_waitcnt vmcnt(9)
	v_cvt_pk_bf16_f32 v2, v62, v63
	s_waitcnt vmcnt(7)
	v_cvt_pk_bf16_f32 v3, v64, v65
.LBB0_794:
	v_readlane_b32 s0, v254, 38
	s_add_i32 s62, s62, s0
	s_add_i32 s12, s12, s20
	s_add_i32 s60, s60, s61
	s_cmpk_lt_i32 s62, 0xec0
	global_store_dwordx4 v[66:67], v[0:3], off offset:112 sc1
	s_cbranch_scc0 .LBB0_818
.LBB0_795:
	s_cmpk_gt_i32 s62, 0x4ff
	s_mov_b64 s[0:1], -1
	s_cbranch_scc0 .LBB0_815
	s_cmpk_gt_u32 s62, 0x53f
	s_cbranch_scc0 .LBB0_812
	s_cmpk_gt_u32 s62, 0x57f
	s_cbranch_scc0 .LBB0_809
	s_cmpk_gt_u32 s62, 0x67f
	s_cbranch_scc0 .LBB0_806
	s_cmpk_gt_u32 s62, 0xbff
	s_cbranch_scc0 .LBB0_801
	s_and_b32 s0, s60, 0x7fffffc0
	s_add_i32 s92, s0, 0xffffd000
	s_and_b32 s0, s12, 0x3c0
	s_lshl_b64 s[28:29], s[92:93], 12
	s_add_u32 s1, s4, s28
	s_addc_u32 s29, s5, s29
	s_lshl_b32 s28, s0, 2
	s_add_u32 s28, s1, s28
	s_addc_u32 s29, s29, 0
	v_lshl_add_u64 v[0:1], v[4:5], 2, s[28:29]
	v_add_co_u32_e32 v8, vcc, s11, v0
	s_movk_i32 s1, 0x4000
	s_nop 0
	v_addc_co_u32_e32 v9, vcc, 0, v1, vcc
	v_add_co_u32_e32 v10, vcc, s1, v0
	s_movk_i32 s1, 0x6000
	s_nop 0
	v_addc_co_u32_e32 v11, vcc, 0, v1, vcc
	v_add_co_u32_e32 v12, vcc, s1, v0
	s_mov_b32 s1, 0x8000
	s_nop 0
	v_addc_co_u32_e32 v13, vcc, 0, v1, vcc
	v_add_co_u32_e32 v14, vcc, s1, v0
	s_mov_b32 s1, 0xa000
	s_nop 0
	v_addc_co_u32_e32 v15, vcc, 0, v1, vcc
	s_waitcnt vmcnt(5)
	v_add_co_u32_e32 v16, vcc, s1, v0
	s_mov_b32 s1, 0xc000
	s_nop 0
	v_addc_co_u32_e32 v17, vcc, 0, v1, vcc
	v_add_co_u32_e32 v18, vcc, s1, v0
	s_mov_b32 s1, 0xe000
	s_nop 0
	v_addc_co_u32_e32 v19, vcc, 0, v1, vcc
	v_add_co_u32_e32 v20, vcc, s1, v0
	s_mov_b32 s1, 0x12000
	s_nop 0
	v_addc_co_u32_e32 v21, vcc, 0, v1, vcc
	v_add_co_u32_e32 v22, vcc, s67, v0
	global_load_dword v2, v[8:9], off offset:-4096
	global_load_dword v3, v[0:1], off
	v_addc_co_u32_e32 v23, vcc, 0, v1, vcc
	global_load_dword v6, v[10:11], off offset:-4096
	global_load_dword v7, v[8:9], off
	s_nop 0
	global_load_dword v8, v[12:13], off offset:-4096
	global_load_dword v9, v[10:11], off
	s_nop 0
	global_load_dword v10, v[14:15], off offset:-4096
	global_load_dword v11, v[12:13], off
	s_nop 0
	global_load_dword v12, v[16:17], off offset:-4096
	global_load_dword v13, v[14:15], off
	s_nop 0
	global_load_dword v14, v[18:19], off offset:-4096
	global_load_dword v15, v[16:17], off
	s_nop 0
	global_load_dword v16, v[20:21], off offset:-4096
	global_load_dword v17, v[18:19], off
	s_nop 0
	global_load_dword v18, v[22:23], off offset:-4096
	global_load_dword v19, v[20:21], off
	v_add_co_u32_e32 v20, vcc, s1, v0
	s_mov_b32 s1, 0x14000
	s_nop 0
	v_addc_co_u32_e32 v21, vcc, 0, v1, vcc
	global_load_dword v24, v[20:21], off offset:-4096
	global_load_dword v25, v[22:23], off
	v_add_co_u32_e32 v22, vcc, s1, v0
	s_mov_b32 s1, 0x16000
	s_nop 0
	v_addc_co_u32_e32 v23, vcc, 0, v1, vcc
	global_load_dword v26, v[22:23], off offset:-4096
	global_load_dword v27, v[20:21], off
	v_add_co_u32_e32 v20, vcc, s1, v0
	s_mov_b32 s1, 0x18000
	s_nop 0
	v_addc_co_u32_e32 v21, vcc, 0, v1, vcc
	global_load_dword v28, v[20:21], off offset:-4096
	global_load_dword v29, v[22:23], off
	v_add_co_u32_e32 v22, vcc, s1, v0
	s_mov_b32 s1, 0x1a000
	s_nop 0
	v_addc_co_u32_e32 v23, vcc, 0, v1, vcc
	global_load_dword v30, v[22:23], off offset:-4096
	global_load_dword v31, v[20:21], off
	v_add_co_u32_e32 v20, vcc, s1, v0
	s_mov_b32 s1, 0x1c000
	s_nop 0
	v_addc_co_u32_e32 v21, vcc, 0, v1, vcc
	global_load_dword v32, v[20:21], off offset:-4096
	global_load_dword v33, v[22:23], off
	v_add_co_u32_e32 v22, vcc, s1, v0
	s_mov_b32 s1, 0x1e000
	s_nop 0
	v_addc_co_u32_e32 v23, vcc, 0, v1, vcc
	global_load_dword v34, v[22:23], off offset:-4096
	global_load_dword v35, v[20:21], off
	v_add_co_u32_e32 v20, vcc, s1, v0
	s_mov_b32 s1, 0x20000
	s_nop 0
	v_addc_co_u32_e32 v21, vcc, 0, v1, vcc
	global_load_dword v36, v[20:21], off offset:-4096
	global_load_dword v37, v[22:23], off
	v_add_co_u32_e32 v22, vcc, s1, v0
	s_mov_b32 s1, 0x22000
	s_nop 0
	v_addc_co_u32_e32 v23, vcc, 0, v1, vcc
	global_load_dword v38, v[22:23], off offset:-4096
	global_load_dword v39, v[20:21], off
	v_add_co_u32_e32 v20, vcc, s1, v0
	s_mov_b32 s1, 0x24000
	s_nop 0
	v_addc_co_u32_e32 v21, vcc, 0, v1, vcc
	global_load_dword v40, v[20:21], off offset:-4096
	global_load_dword v41, v[22:23], off
	v_add_co_u32_e32 v22, vcc, s1, v0
	s_mov_b32 s1, 0x26000
	s_nop 0
	v_addc_co_u32_e32 v23, vcc, 0, v1, vcc
	global_load_dword v42, v[22:23], off offset:-4096
	global_load_dword v43, v[20:21], off
	v_add_co_u32_e32 v20, vcc, s1, v0
	s_mov_b32 s1, 0x2a000
	s_nop 0
	v_addc_co_u32_e32 v21, vcc, 0, v1, vcc
	global_load_dword v44, v[20:21], off offset:-4096
	global_load_dword v45, v[22:23], off
	v_add_co_u32_e32 v22, vcc, s95, v0
	s_nop 1
	v_addc_co_u32_e32 v23, vcc, 0, v1, vcc
	global_load_dword v46, v[22:23], off offset:-4096
	global_load_dword v47, v[20:21], off
	v_add_co_u32_e32 v20, vcc, s1, v0
	s_mov_b32 s1, 0x2c000
	s_nop 0
	v_addc_co_u32_e32 v21, vcc, 0, v1, vcc
	global_load_dword v48, v[20:21], off offset:-4096
	global_load_dword v49, v[22:23], off
	v_add_co_u32_e32 v22, vcc, s1, v0
	s_mov_b32 s1, 0x2e000
	s_nop 0
	v_addc_co_u32_e32 v23, vcc, 0, v1, vcc
	global_load_dword v50, v[22:23], off offset:-4096
	global_load_dword v51, v[20:21], off
	v_add_co_u32_e32 v20, vcc, s1, v0
	s_mov_b32 s1, 0x30000
	s_nop 0
	v_addc_co_u32_e32 v21, vcc, 0, v1, vcc
	global_load_dword v52, v[20:21], off offset:-4096
	global_load_dword v53, v[22:23], off
	v_add_co_u32_e32 v22, vcc, s1, v0
	s_mov_b32 s1, 0x32000
	s_nop 0
	v_addc_co_u32_e32 v23, vcc, 0, v1, vcc
	global_load_dword v54, v[22:23], off offset:-4096
	global_load_dword v55, v[20:21], off
	v_add_co_u32_e32 v20, vcc, s1, v0
	s_mov_b32 s1, 0x34000
	s_nop 0
	v_addc_co_u32_e32 v21, vcc, 0, v1, vcc
	global_load_dword v56, v[20:21], off offset:-4096
	global_load_dword v57, v[22:23], off
	v_add_co_u32_e32 v22, vcc, s1, v0
	s_mov_b32 s1, 0x36000
	s_nop 0
	v_addc_co_u32_e32 v23, vcc, 0, v1, vcc
	global_load_dword v58, v[22:23], off offset:-4096
	global_load_dword v59, v[20:21], off
	v_add_co_u32_e32 v20, vcc, s1, v0
	s_mov_b32 s1, 0x38000
	s_nop 0
	v_addc_co_u32_e32 v21, vcc, 0, v1, vcc
	global_load_dword v60, v[20:21], off offset:-4096
	global_load_dword v61, v[22:23], off
	v_add_co_u32_e32 v22, vcc, s1, v0
	s_mov_b32 s1, 0x3a000
	s_nop 0
	v_addc_co_u32_e32 v23, vcc, 0, v1, vcc
	global_load_dword v62, v[22:23], off offset:-4096
	global_load_dword v63, v[20:21], off
	v_add_co_u32_e32 v20, vcc, s1, v0
	s_mov_b32 s1, 0x3c000
	s_nop 0
	v_addc_co_u32_e32 v21, vcc, 0, v1, vcc
	global_load_dword v64, v[20:21], off offset:-4096
	global_load_dword v65, v[22:23], off
	v_add_co_u32_e32 v22, vcc, s1, v0
	s_mov_b32 s1, 0x3e000
	s_nop 0
	v_addc_co_u32_e32 v23, vcc, 0, v1, vcc
	global_load_dword v68, v[22:23], off offset:-4096
	global_load_dword v69, v[20:21], off
	v_add_co_u32_e32 v20, vcc, s1, v0
	s_mov_b32 s1, 0x3f000
	s_nop 0
	v_addc_co_u32_e32 v21, vcc, 0, v1, vcc
	v_add_co_u32_e32 v0, vcc, s1, v0
	global_load_dword v70, v[20:21], off offset:-4096
	s_nop 0
	global_load_dword v22, v[22:23], off
	v_addc_co_u32_e32 v1, vcc, 0, v1, vcc
	global_load_dword v23, v[0:1], off
	s_nop 0
	global_load_dword v20, v[20:21], off
	v_add_u32_e32 v21, s0, v4
	v_mov_b64_e32 v[0:1], s[44:45]
	v_mad_i64_i32 v[0:1], s[0:1], v21, s25, v[0:1]
	v_lshl_add_u64 v[66:67], s[92:93], 1, v[0:1]
	s_waitcnt vmcnt(62)
	v_cvt_pk_bf16_f32 v0, v3, v2
	s_waitcnt vmcnt(60)
	v_cvt_pk_bf16_f32 v1, v7, v6
	s_waitcnt vmcnt(58)
	v_cvt_pk_bf16_f32 v2, v9, v8
	s_waitcnt vmcnt(56)
	v_cvt_pk_bf16_f32 v3, v11, v10
	global_store_dwordx4 v[66:67], v[0:3], off sc1
	s_mov_b64 s[0:1], 0
	s_waitcnt vmcnt(55)
	v_cvt_pk_bf16_f32 v0, v13, v12
	s_waitcnt vmcnt(53)
	v_cvt_pk_bf16_f32 v1, v15, v14
	s_waitcnt vmcnt(51)
	v_cvt_pk_bf16_f32 v2, v17, v16
	s_waitcnt vmcnt(49)
	v_cvt_pk_bf16_f32 v3, v19, v18
	global_store_dwordx4 v[66:67], v[0:3], off offset:16 sc1
	s_waitcnt vmcnt(48)
	s_nop 0
	v_cvt_pk_bf16_f32 v0, v25, v24
	s_waitcnt vmcnt(46)
	v_cvt_pk_bf16_f32 v1, v27, v26
	s_waitcnt vmcnt(44)
	v_cvt_pk_bf16_f32 v2, v29, v28
	s_waitcnt vmcnt(42)
	v_cvt_pk_bf16_f32 v3, v31, v30
	global_store_dwordx4 v[66:67], v[0:3], off offset:32 sc1
	s_waitcnt vmcnt(41)
	s_nop 0
	v_cvt_pk_bf16_f32 v0, v33, v32
	s_waitcnt vmcnt(39)
	v_cvt_pk_bf16_f32 v1, v35, v34
	s_waitcnt vmcnt(37)
	v_cvt_pk_bf16_f32 v2, v37, v36
	s_waitcnt vmcnt(35)
	v_cvt_pk_bf16_f32 v3, v39, v38
	global_store_dwordx4 v[66:67], v[0:3], off offset:48 sc1
	s_waitcnt vmcnt(34)
	s_nop 0
	v_cvt_pk_bf16_f32 v0, v41, v40
	s_waitcnt vmcnt(32)
	v_cvt_pk_bf16_f32 v1, v43, v42
	s_waitcnt vmcnt(30)
	v_cvt_pk_bf16_f32 v2, v45, v44
	s_waitcnt vmcnt(28)
	v_cvt_pk_bf16_f32 v3, v47, v46
	global_store_dwordx4 v[66:67], v[0:3], off offset:64 sc1
	s_waitcnt vmcnt(27)
	s_nop 0
	v_cvt_pk_bf16_f32 v0, v49, v48
	s_waitcnt vmcnt(25)
	v_cvt_pk_bf16_f32 v1, v51, v50
	s_waitcnt vmcnt(23)
	v_cvt_pk_bf16_f32 v2, v53, v52
	s_waitcnt vmcnt(21)
	v_cvt_pk_bf16_f32 v3, v55, v54
	global_store_dwordx4 v[66:67], v[0:3], off offset:80 sc1
	s_waitcnt vmcnt(20)
	s_nop 0
	v_cvt_pk_bf16_f32 v0, v57, v56
	s_waitcnt vmcnt(18)
	v_cvt_pk_bf16_f32 v1, v59, v58
	s_waitcnt vmcnt(16)
	v_cvt_pk_bf16_f32 v2, v61, v60
	s_waitcnt vmcnt(14)
	v_cvt_pk_bf16_f32 v3, v63, v62
	global_store_dwordx4 v[66:67], v[0:3], off offset:96 sc1
	s_waitcnt vmcnt(13)
	s_nop 0
	v_cvt_pk_bf16_f32 v0, v65, v64
	s_waitcnt vmcnt(11)
	v_cvt_pk_bf16_f32 v1, v69, v68
	s_waitcnt vmcnt(9)
	v_cvt_pk_bf16_f32 v2, v22, v70
	s_waitcnt vmcnt(7)
	v_cvt_pk_bf16_f32 v3, v20, v23

.LBB0_804:
	s_lshl_b32 s28, s1, 6
	s_and_b32 s28, 0xffff, s28
	s_and_b32 s1, 0xffff, s1
	s_add_i32 s29, s28, 0xfffff500
	s_cmp_lt_u32 s1, 44
	s_cselect_b32 s1, s28, s29
	s_cselect_b32 s28, 0, 0x80
	s_lshl_b32 s29, s1, 1
	s_and_b32 s29, s29, 0xffffff00
	s_and_b32 s1, s1, 64
	s_or_b32 s1, s29, s1
	s_or_b32 s1, s1, s28
	v_add_u32_e32 v66, s1, v4
	v_ashrrev_i32_e32 v67, 31, v66
	v_lshlrev_b64 v[66:67], 11, v[66:67]
	v_lshl_add_u64 v[66:67], s[48:49], 0, v[66:67]
	s_lshl_b32 s92, s0, 1
	v_lshl_add_u64 v[66:67], v[66:67], 0, s[92:93]
	s_waitcnt vmcnt(62)
	v_cvt_pk_bf16_f32 v0, v0, v1
	s_waitcnt vmcnt(60)
	v_cvt_pk_bf16_f32 v1, v2, v3
	s_waitcnt vmcnt(58)
	v_cvt_pk_bf16_f32 v2, v6, v7
	s_waitcnt vmcnt(56)
	v_cvt_pk_bf16_f32 v3, v8, v9
	global_store_dwordx4 v[66:67], v[0:3], off sc1
	s_waitcnt vmcnt(55)
	s_nop 0
	v_cvt_pk_bf16_f32 v0, v10, v11
	s_waitcnt vmcnt(53)
	v_cvt_pk_bf16_f32 v1, v12, v13
	s_waitcnt vmcnt(51)
	v_cvt_pk_bf16_f32 v2, v14, v15
	s_waitcnt vmcnt(49)
	v_cvt_pk_bf16_f32 v3, v16, v17
	global_store_dwordx4 v[66:67], v[0:3], off offset:16 sc1
	s_waitcnt vmcnt(48)
	s_nop 0
	v_cvt_pk_bf16_f32 v0, v18, v19
	s_waitcnt vmcnt(46)
	v_cvt_pk_bf16_f32 v1, v20, v21
	s_waitcnt vmcnt(44)
	v_cvt_pk_bf16_f32 v2, v22, v23
	s_waitcnt vmcnt(42)
	v_cvt_pk_bf16_f32 v3, v24, v25
	global_store_dwordx4 v[66:67], v[0:3], off offset:32 sc1
	s_waitcnt vmcnt(41)
	s_nop 0
	v_cvt_pk_bf16_f32 v0, v26, v27
	s_waitcnt vmcnt(39)
	v_cvt_pk_bf16_f32 v1, v28, v29
	s_waitcnt vmcnt(37)
	v_cvt_pk_bf16_f32 v2, v30, v31
	s_waitcnt vmcnt(35)
	v_cvt_pk_bf16_f32 v3, v32, v33
	global_store_dwordx4 v[66:67], v[0:3], off offset:48 sc1
	s_waitcnt vmcnt(34)
	s_nop 0
	v_cvt_pk_bf16_f32 v0, v34, v35
	s_waitcnt vmcnt(32)
	v_cvt_pk_bf16_f32 v1, v36, v37
	s_waitcnt vmcnt(30)
	v_cvt_pk_bf16_f32 v2, v38, v39
	s_waitcnt vmcnt(28)
	v_cvt_pk_bf16_f32 v3, v40, v41
	global_store_dwordx4 v[66:67], v[0:3], off offset:64 sc1
	s_waitcnt vmcnt(27)
	s_nop 0
	v_cvt_pk_bf16_f32 v0, v42, v43
	s_waitcnt vmcnt(25)
	v_cvt_pk_bf16_f32 v1, v44, v45
	s_waitcnt vmcnt(23)
	v_cvt_pk_bf16_f32 v2, v46, v47
	s_waitcnt vmcnt(21)
	v_cvt_pk_bf16_f32 v3, v48, v49
	global_store_dwordx4 v[66:67], v[0:3], off offset:80 sc1
	s_waitcnt vmcnt(20)
	s_nop 0
	v_cvt_pk_bf16_f32 v0, v50, v51
	s_waitcnt vmcnt(18)
	v_cvt_pk_bf16_f32 v1, v52, v53
	s_waitcnt vmcnt(16)
	v_cvt_pk_bf16_f32 v2, v54, v55
	s_waitcnt vmcnt(14)
	v_cvt_pk_bf16_f32 v3, v56, v57
	global_store_dwordx4 v[66:67], v[0:3], off offset:96 sc1
	s_waitcnt vmcnt(13)
	s_nop 0
	v_cvt_pk_bf16_f32 v0, v58, v59
	s_waitcnt vmcnt(11)
	v_cvt_pk_bf16_f32 v1, v60, v61
	s_waitcnt vmcnt(9)
	v_cvt_pk_bf16_f32 v2, v62, v63
	s_waitcnt vmcnt(7)
	v_cvt_pk_bf16_f32 v3, v64, v65

.LBB0_806:
	s_andn2_b64 vcc, exec, s[0:1]
	s_cbranch_vccnz .LBB0_808
	s_and_b32 s0, s60, 0x3c0
	s_xor_b32 s0, s0, 0x200
	s_and_b32 s1, s12, 0x3c0
	s_lshl_b32 s28, s0, 12
	s_add_u32 s28, s27, s28
	s_addc_u32 s29, s36, 0
	s_lshl_b32 s30, s1, 2
	s_add_u32 s28, s28, s30
	s_addc_u32 s29, s29, 0
	v_lshl_add_u64 v[0:1], v[4:5], 2, s[28:29]
	v_add_co_u32_e32 v8, vcc, s11, v0
	s_movk_i32 s28, 0x4000
	s_nop 0
	v_addc_co_u32_e32 v9, vcc, 0, v1, vcc
	v_add_co_u32_e32 v10, vcc, s28, v0
	s_movk_i32 s28, 0x6000
	s_nop 0
	v_addc_co_u32_e32 v11, vcc, 0, v1, vcc
	v_add_co_u32_e32 v12, vcc, s28, v0
	s_mov_b32 s28, 0x8000
	s_nop 0
	v_addc_co_u32_e32 v13, vcc, 0, v1, vcc
	v_add_co_u32_e32 v14, vcc, s28, v0
	s_mov_b32 s28, 0xa000
	s_nop 0
	v_addc_co_u32_e32 v15, vcc, 0, v1, vcc
	s_waitcnt vmcnt(5)
	v_add_co_u32_e32 v16, vcc, s28, v0
	s_mov_b32 s28, 0xc000
	s_nop 0
	v_addc_co_u32_e32 v17, vcc, 0, v1, vcc
	v_add_co_u32_e32 v18, vcc, s28, v0
	s_mov_b32 s28, 0xe000
	s_nop 0
	v_addc_co_u32_e32 v19, vcc, 0, v1, vcc
	v_add_co_u32_e32 v20, vcc, s28, v0
	s_mov_b32 s28, 0x12000
	s_nop 0
	v_addc_co_u32_e32 v21, vcc, 0, v1, vcc
	v_add_co_u32_e32 v22, vcc, s67, v0
	global_load_dword v2, v[8:9], off offset:-4096
	global_load_dword v3, v[0:1], off
	v_addc_co_u32_e32 v23, vcc, 0, v1, vcc
	global_load_dword v6, v[10:11], off offset:-4096
	global_load_dword v7, v[8:9], off
	s_nop 0
	global_load_dword v8, v[12:13], off offset:-4096
	global_load_dword v9, v[10:11], off
	s_nop 0
	global_load_dword v10, v[14:15], off offset:-4096
	global_load_dword v11, v[12:13], off
	s_nop 0
	global_load_dword v12, v[16:17], off offset:-4096
	global_load_dword v13, v[14:15], off
	s_nop 0
	global_load_dword v14, v[18:19], off offset:-4096
	global_load_dword v15, v[16:17], off
	s_nop 0
	global_load_dword v16, v[20:21], off offset:-4096
	global_load_dword v17, v[18:19], off
	s_nop 0
	global_load_dword v18, v[22:23], off offset:-4096
	global_load_dword v19, v[20:21], off
	v_add_co_u32_e32 v20, vcc, s28, v0
	s_mov_b32 s28, 0x14000
	s_nop 0
	v_addc_co_u32_e32 v21, vcc, 0, v1, vcc
	global_load_dword v24, v[20:21], off offset:-4096
	global_load_dword v25, v[22:23], off
	v_add_co_u32_e32 v22, vcc, s28, v0
	s_mov_b32 s28, 0x16000
	s_nop 0
	v_addc_co_u32_e32 v23, vcc, 0, v1, vcc
	global_load_dword v26, v[22:23], off offset:-4096
	global_load_dword v27, v[20:21], off
	v_add_co_u32_e32 v20, vcc, s28, v0
	s_mov_b32 s28, 0x18000
	s_nop 0
	v_addc_co_u32_e32 v21, vcc, 0, v1, vcc
	global_load_dword v28, v[20:21], off offset:-4096
	global_load_dword v29, v[22:23], off
	v_add_co_u32_e32 v22, vcc, s28, v0
	s_mov_b32 s28, 0x1a000
	s_nop 0
	v_addc_co_u32_e32 v23, vcc, 0, v1, vcc
	global_load_dword v30, v[22:23], off offset:-4096
	global_load_dword v31, v[20:21], off
	v_add_co_u32_e32 v20, vcc, s28, v0
	s_mov_b32 s28, 0x1c000
	s_nop 0
	v_addc_co_u32_e32 v21, vcc, 0, v1, vcc
	global_load_dword v32, v[20:21], off offset:-4096
	global_load_dword v33, v[22:23], off
	v_add_co_u32_e32 v22, vcc, s28, v0
	s_mov_b32 s28, 0x1e000
	s_nop 0
	v_addc_co_u32_e32 v23, vcc, 0, v1, vcc
	global_load_dword v34, v[22:23], off offset:-4096
	global_load_dword v35, v[20:21], off
	v_add_co_u32_e32 v20, vcc, s28, v0
	s_mov_b32 s28, 0x20000
	s_nop 0
	v_addc_co_u32_e32 v21, vcc, 0, v1, vcc
	global_load_dword v36, v[20:21], off offset:-4096
	global_load_dword v37, v[22:23], off
	v_add_co_u32_e32 v22, vcc, s28, v0
	s_mov_b32 s28, 0x22000
	s_nop 0
	v_addc_co_u32_e32 v23, vcc, 0, v1, vcc
	global_load_dword v38, v[22:23], off offset:-4096
	global_load_dword v39, v[20:21], off
	v_add_co_u32_e32 v20, vcc, s28, v0
	s_mov_b32 s28, 0x24000
	s_nop 0
	v_addc_co_u32_e32 v21, vcc, 0, v1, vcc
	global_load_dword v40, v[20:21], off offset:-4096
	global_load_dword v41, v[22:23], off
	v_add_co_u32_e32 v22, vcc, s28, v0
	s_mov_b32 s28, 0x26000
	s_nop 0
	v_addc_co_u32_e32 v23, vcc, 0, v1, vcc
	global_load_dword v42, v[22:23], off offset:-4096
	global_load_dword v43, v[20:21], off
	v_add_co_u32_e32 v20, vcc, s28, v0
	s_mov_b32 s28, 0x2a000
	s_nop 0
	v_addc_co_u32_e32 v21, vcc, 0, v1, vcc
	global_load_dword v44, v[20:21], off offset:-4096
	global_load_dword v45, v[22:23], off
	v_add_co_u32_e32 v22, vcc, s95, v0
	s_lshl_b32 s92, s0, 1
	s_nop 0
	v_addc_co_u32_e32 v23, vcc, 0, v1, vcc
	global_load_dword v46, v[22:23], off offset:-4096
	global_load_dword v47, v[20:21], off
	v_add_co_u32_e32 v20, vcc, s28, v0
	s_mov_b32 s28, 0x2c000
	s_nop 0
	v_addc_co_u32_e32 v21, vcc, 0, v1, vcc
	global_load_dword v48, v[20:21], off offset:-4096
	global_load_dword v49, v[22:23], off
	v_add_co_u32_e32 v22, vcc, s28, v0
	s_mov_b32 s28, 0x2e000
	s_nop 0
	v_addc_co_u32_e32 v23, vcc, 0, v1, vcc
	global_load_dword v50, v[22:23], off offset:-4096
	global_load_dword v51, v[20:21], off
	v_add_co_u32_e32 v20, vcc, s28, v0
	s_mov_b32 s28, 0x30000
	s_nop 0
	v_addc_co_u32_e32 v21, vcc, 0, v1, vcc
	global_load_dword v52, v[20:21], off offset:-4096
	global_load_dword v53, v[22:23], off
	v_add_co_u32_e32 v22, vcc, s28, v0
	s_mov_b32 s28, 0x32000
	s_nop 0
	v_addc_co_u32_e32 v23, vcc, 0, v1, vcc
	global_load_dword v54, v[22:23], off offset:-4096
	global_load_dword v55, v[20:21], off
	v_add_co_u32_e32 v20, vcc, s28, v0
	s_mov_b32 s28, 0x34000
	s_nop 0
	v_addc_co_u32_e32 v21, vcc, 0, v1, vcc
	global_load_dword v56, v[20:21], off offset:-4096
	global_load_dword v57, v[22:23], off
	v_add_co_u32_e32 v22, vcc, s28, v0
	s_mov_b32 s28, 0x36000
	s_nop 0
	v_addc_co_u32_e32 v23, vcc, 0, v1, vcc
	global_load_dword v58, v[22:23], off offset:-4096
	global_load_dword v59, v[20:21], off
	v_add_co_u32_e32 v20, vcc, s28, v0
	s_mov_b32 s28, 0x38000
	s_nop 0
	v_addc_co_u32_e32 v21, vcc, 0, v1, vcc
	global_load_dword v60, v[20:21], off offset:-4096
	global_load_dword v61, v[22:23], off
	v_add_co_u32_e32 v22, vcc, s28, v0
	s_mov_b32 s28, 0x3a000
	s_nop 0
	v_addc_co_u32_e32 v23, vcc, 0, v1, vcc
	global_load_dword v62, v[22:23], off offset:-4096
	global_load_dword v63, v[20:21], off
	v_add_co_u32_e32 v20, vcc, s28, v0
	s_mov_b32 s28, 0x3c000
	s_nop 0
	v_addc_co_u32_e32 v21, vcc, 0, v1, vcc
	global_load_dword v64, v[20:21], off offset:-4096
	global_load_dword v65, v[22:23], off
	v_add_co_u32_e32 v22, vcc, s28, v0
	s_mov_b32 s28, 0x3e000
	s_nop 0
	v_addc_co_u32_e32 v23, vcc, 0, v1, vcc
	global_load_dword v68, v[22:23], off offset:-4096
	global_load_dword v69, v[20:21], off
	v_add_co_u32_e32 v20, vcc, s28, v0
	s_mov_b32 s28, 0x3f000
	s_nop 0
	v_addc_co_u32_e32 v21, vcc, 0, v1, vcc
	v_add_co_u32_e32 v0, vcc, s28, v0
	global_load_dword v70, v[20:21], off offset:-4096
	s_nop 0
	global_load_dword v22, v[22:23], off
	v_addc_co_u32_e32 v1, vcc, 0, v1, vcc
	global_load_dword v23, v[0:1], off
	s_nop 0
	global_load_dword v20, v[20:21], off
	v_add_u32_e32 v0, s1, v4
	v_ashrrev_i32_e32 v1, 31, v0
	v_lshlrev_b64 v[0:1], 11, v[0:1]
	v_lshl_add_u64 v[0:1], s[50:51], 0, v[0:1]
	v_lshl_add_u64 v[66:67], v[0:1], 0, s[92:93]
	s_waitcnt vmcnt(62)
	v_cvt_pk_bf16_f32 v0, v3, v2
	s_waitcnt vmcnt(60)
	v_cvt_pk_bf16_f32 v1, v7, v6
	s_waitcnt vmcnt(58)
	v_cvt_pk_bf16_f32 v2, v9, v8
	s_waitcnt vmcnt(56)
	v_cvt_pk_bf16_f32 v3, v11, v10
	global_store_dwordx4 v[66:67], v[0:3], off sc1
	s_waitcnt vmcnt(55)
	s_nop 0
	v_cvt_pk_bf16_f32 v0, v13, v12
	s_waitcnt vmcnt(53)
	v_cvt_pk_bf16_f32 v1, v15, v14
	s_waitcnt vmcnt(51)
	v_cvt_pk_bf16_f32 v2, v17, v16
	s_waitcnt vmcnt(49)
	v_cvt_pk_bf16_f32 v3, v19, v18
	global_store_dwordx4 v[66:67], v[0:3], off offset:16 sc1
	s_waitcnt vmcnt(48)
	s_nop 0
	v_cvt_pk_bf16_f32 v0, v25, v24
	s_waitcnt vmcnt(46)
	v_cvt_pk_bf16_f32 v1, v27, v26
	s_waitcnt vmcnt(44)
	v_cvt_pk_bf16_f32 v2, v29, v28
	s_waitcnt vmcnt(42)
	v_cvt_pk_bf16_f32 v3, v31, v30
	global_store_dwordx4 v[66:67], v[0:3], off offset:32 sc1
	s_waitcnt vmcnt(41)
	s_nop 0
	v_cvt_pk_bf16_f32 v0, v33, v32
	s_waitcnt vmcnt(39)
	v_cvt_pk_bf16_f32 v1, v35, v34
	s_waitcnt vmcnt(37)
	v_cvt_pk_bf16_f32 v2, v37, v36
	s_waitcnt vmcnt(35)
	v_cvt_pk_bf16_f32 v3, v39, v38
	global_store_dwordx4 v[66:67], v[0:3], off offset:48 sc1
	s_waitcnt vmcnt(34)
	s_nop 0
	v_cvt_pk_bf16_f32 v0, v41, v40
	s_waitcnt vmcnt(32)
	v_cvt_pk_bf16_f32 v1, v43, v42
	s_waitcnt vmcnt(30)
	v_cvt_pk_bf16_f32 v2, v45, v44
	s_waitcnt vmcnt(28)
	v_cvt_pk_bf16_f32 v3, v47, v46
	global_store_dwordx4 v[66:67], v[0:3], off offset:64 sc1
	s_waitcnt vmcnt(27)
	s_nop 0
	v_cvt_pk_bf16_f32 v0, v49, v48
	s_waitcnt vmcnt(25)
	v_cvt_pk_bf16_f32 v1, v51, v50
	s_waitcnt vmcnt(23)
	v_cvt_pk_bf16_f32 v2, v53, v52
	s_waitcnt vmcnt(21)
	v_cvt_pk_bf16_f32 v3, v55, v54
	global_store_dwordx4 v[66:67], v[0:3], off offset:80 sc1
	s_waitcnt vmcnt(20)
	s_nop 0
	v_cvt_pk_bf16_f32 v0, v57, v56
	s_waitcnt vmcnt(18)
	v_cvt_pk_bf16_f32 v1, v59, v58
	s_waitcnt vmcnt(16)
	v_cvt_pk_bf16_f32 v2, v61, v60
	s_waitcnt vmcnt(14)
	v_cvt_pk_bf16_f32 v3, v63, v62
	global_store_dwordx4 v[66:67], v[0:3], off offset:96 sc1
	s_waitcnt vmcnt(13)
	s_nop 0
	v_cvt_pk_bf16_f32 v0, v65, v64
	s_waitcnt vmcnt(11)
	v_cvt_pk_bf16_f32 v1, v69, v68
	s_waitcnt vmcnt(9)
	v_cvt_pk_bf16_f32 v2, v22, v70
	s_waitcnt vmcnt(7)
	v_cvt_pk_bf16_f32 v3, v20, v23

.LBB0_809:
	s_andn2_b64 vcc, exec, s[0:1]
	s_cbranch_vccnz .LBB0_811
	s_add_i32 s0, s60, 0x300
	s_and_b32 s0, s0, 0x3c0
	s_and_b32 s1, s12, 0x3c0
	s_lshl_b32 s28, s0, 12
	s_add_u32 s28, s37, s28
	s_addc_u32 s29, s38, 0
	s_lshl_b32 s30, s1, 2
	s_add_u32 s28, s28, s30
	s_addc_u32 s29, s29, 0
	v_lshl_add_u64 v[0:1], v[4:5], 2, s[28:29]
	v_add_co_u32_e32 v8, vcc, s11, v0
	s_movk_i32 s28, 0x4000
	s_nop 0
	v_addc_co_u32_e32 v9, vcc, 0, v1, vcc
	v_add_co_u32_e32 v10, vcc, s28, v0
	s_movk_i32 s28, 0x6000
	s_nop 0
	v_addc_co_u32_e32 v11, vcc, 0, v1, vcc
	v_add_co_u32_e32 v12, vcc, s28, v0
	s_mov_b32 s28, 0x8000
	s_nop 0
	v_addc_co_u32_e32 v13, vcc, 0, v1, vcc
	v_add_co_u32_e32 v14, vcc, s28, v0
	s_mov_b32 s28, 0xa000
	s_nop 0
	v_addc_co_u32_e32 v15, vcc, 0, v1, vcc
	s_waitcnt vmcnt(5)
	v_add_co_u32_e32 v16, vcc, s28, v0
	s_mov_b32 s28, 0xc000
	s_nop 0
	v_addc_co_u32_e32 v17, vcc, 0, v1, vcc
	v_add_co_u32_e32 v18, vcc, s28, v0
	s_mov_b32 s28, 0xe000
	s_nop 0
	v_addc_co_u32_e32 v19, vcc, 0, v1, vcc
	v_add_co_u32_e32 v20, vcc, s28, v0
	s_mov_b32 s28, 0x12000
	s_nop 0
	v_addc_co_u32_e32 v21, vcc, 0, v1, vcc
	v_add_co_u32_e32 v22, vcc, s67, v0
	global_load_dword v2, v[8:9], off offset:-4096
	global_load_dword v3, v[0:1], off
	v_addc_co_u32_e32 v23, vcc, 0, v1, vcc
	global_load_dword v6, v[10:11], off offset:-4096
	global_load_dword v7, v[8:9], off
	s_nop 0
	global_load_dword v8, v[12:13], off offset:-4096
	global_load_dword v9, v[10:11], off
	s_nop 0
	global_load_dword v10, v[14:15], off offset:-4096
	global_load_dword v11, v[12:13], off
	s_nop 0
	global_load_dword v12, v[16:17], off offset:-4096
	global_load_dword v13, v[14:15], off
	s_nop 0
	global_load_dword v14, v[18:19], off offset:-4096
	global_load_dword v15, v[16:17], off
	s_nop 0
	global_load_dword v16, v[20:21], off offset:-4096
	global_load_dword v17, v[18:19], off
	s_nop 0
	global_load_dword v18, v[22:23], off offset:-4096
	global_load_dword v19, v[20:21], off
	v_add_co_u32_e32 v20, vcc, s28, v0
	s_mov_b32 s28, 0x14000
	s_nop 0
	v_addc_co_u32_e32 v21, vcc, 0, v1, vcc
	global_load_dword v24, v[20:21], off offset:-4096
	global_load_dword v25, v[22:23], off
	v_add_co_u32_e32 v22, vcc, s28, v0
	s_mov_b32 s28, 0x16000
	s_nop 0
	v_addc_co_u32_e32 v23, vcc, 0, v1, vcc
	global_load_dword v26, v[22:23], off offset:-4096
	global_load_dword v27, v[20:21], off
	v_add_co_u32_e32 v20, vcc, s28, v0
	s_mov_b32 s28, 0x18000
	s_nop 0
	v_addc_co_u32_e32 v21, vcc, 0, v1, vcc
	global_load_dword v28, v[20:21], off offset:-4096
	global_load_dword v29, v[22:23], off
	v_add_co_u32_e32 v22, vcc, s28, v0
	s_mov_b32 s28, 0x1a000
	s_nop 0
	v_addc_co_u32_e32 v23, vcc, 0, v1, vcc
	global_load_dword v30, v[22:23], off offset:-4096
	global_load_dword v31, v[20:21], off
	v_add_co_u32_e32 v20, vcc, s28, v0
	s_mov_b32 s28, 0x1c000
	s_nop 0
	v_addc_co_u32_e32 v21, vcc, 0, v1, vcc
	global_load_dword v32, v[20:21], off offset:-4096
	global_load_dword v33, v[22:23], off
	v_add_co_u32_e32 v22, vcc, s28, v0
	s_mov_b32 s28, 0x1e000
	s_nop 0
	v_addc_co_u32_e32 v23, vcc, 0, v1, vcc
	global_load_dword v34, v[22:23], off offset:-4096
	global_load_dword v35, v[20:21], off
	v_add_co_u32_e32 v20, vcc, s28, v0
	s_mov_b32 s28, 0x20000
	s_nop 0
	v_addc_co_u32_e32 v21, vcc, 0, v1, vcc
	global_load_dword v36, v[20:21], off offset:-4096
	global_load_dword v37, v[22:23], off
	v_add_co_u32_e32 v22, vcc, s28, v0
	s_mov_b32 s28, 0x22000
	s_nop 0
	v_addc_co_u32_e32 v23, vcc, 0, v1, vcc
	global_load_dword v38, v[22:23], off offset:-4096
	global_load_dword v39, v[20:21], off
	v_add_co_u32_e32 v20, vcc, s28, v0
	s_mov_b32 s28, 0x24000
	s_nop 0
	v_addc_co_u32_e32 v21, vcc, 0, v1, vcc
	global_load_dword v40, v[20:21], off offset:-4096
	global_load_dword v41, v[22:23], off
	v_add_co_u32_e32 v22, vcc, s28, v0
	s_mov_b32 s28, 0x26000
	s_nop 0
	v_addc_co_u32_e32 v23, vcc, 0, v1, vcc
	global_load_dword v42, v[22:23], off offset:-4096
	global_load_dword v43, v[20:21], off
	v_add_co_u32_e32 v20, vcc, s28, v0
	s_mov_b32 s28, 0x2a000
	s_nop 0
	v_addc_co_u32_e32 v21, vcc, 0, v1, vcc
	global_load_dword v44, v[20:21], off offset:-4096
	global_load_dword v45, v[22:23], off
	v_add_co_u32_e32 v22, vcc, s95, v0
	s_lshl_b32 s92, s0, 1
	s_nop 0
	v_addc_co_u32_e32 v23, vcc, 0, v1, vcc
	global_load_dword v46, v[22:23], off offset:-4096
	global_load_dword v47, v[20:21], off
	v_add_co_u32_e32 v20, vcc, s28, v0
	s_mov_b32 s28, 0x2c000
	s_nop 0
	v_addc_co_u32_e32 v21, vcc, 0, v1, vcc
	global_load_dword v48, v[20:21], off offset:-4096
	global_load_dword v49, v[22:23], off
	v_add_co_u32_e32 v22, vcc, s28, v0
	s_mov_b32 s28, 0x2e000
	s_nop 0
	v_addc_co_u32_e32 v23, vcc, 0, v1, vcc
	global_load_dword v50, v[22:23], off offset:-4096
	global_load_dword v51, v[20:21], off
	v_add_co_u32_e32 v20, vcc, s28, v0
	s_mov_b32 s28, 0x30000
	s_nop 0
	v_addc_co_u32_e32 v21, vcc, 0, v1, vcc
	global_load_dword v52, v[20:21], off offset:-4096
	global_load_dword v53, v[22:23], off
	v_add_co_u32_e32 v22, vcc, s28, v0
	s_mov_b32 s28, 0x32000
	s_nop 0
	v_addc_co_u32_e32 v23, vcc, 0, v1, vcc
	global_load_dword v54, v[22:23], off offset:-4096
	global_load_dword v55, v[20:21], off
	v_add_co_u32_e32 v20, vcc, s28, v0
	s_mov_b32 s28, 0x34000
	s_nop 0
	v_addc_co_u32_e32 v21, vcc, 0, v1, vcc
	global_load_dword v56, v[20:21], off offset:-4096
	global_load_dword v57, v[22:23], off
	v_add_co_u32_e32 v22, vcc, s28, v0
	s_mov_b32 s28, 0x36000
	s_nop 0
	v_addc_co_u32_e32 v23, vcc, 0, v1, vcc
	global_load_dword v58, v[22:23], off offset:-4096
	global_load_dword v59, v[20:21], off
	v_add_co_u32_e32 v20, vcc, s28, v0
	s_mov_b32 s28, 0x38000
	s_nop 0
	v_addc_co_u32_e32 v21, vcc, 0, v1, vcc
	global_load_dword v60, v[20:21], off offset:-4096
	global_load_dword v61, v[22:23], off
	v_add_co_u32_e32 v22, vcc, s28, v0
	s_mov_b32 s28, 0x3a000
	s_nop 0
	v_addc_co_u32_e32 v23, vcc, 0, v1, vcc
	global_load_dword v62, v[22:23], off offset:-4096
	global_load_dword v63, v[20:21], off
	v_add_co_u32_e32 v20, vcc, s28, v0
	s_mov_b32 s28, 0x3c000
	s_nop 0
	v_addc_co_u32_e32 v21, vcc, 0, v1, vcc
	global_load_dword v64, v[20:21], off offset:-4096
	global_load_dword v65, v[22:23], off
	v_add_co_u32_e32 v22, vcc, s28, v0
	s_mov_b32 s28, 0x3e000
	s_nop 0
	v_addc_co_u32_e32 v23, vcc, 0, v1, vcc
	global_load_dword v68, v[22:23], off offset:-4096
	global_load_dword v69, v[20:21], off
	v_add_co_u32_e32 v20, vcc, s28, v0
	s_mov_b32 s28, 0x3f000
	s_nop 0
	v_addc_co_u32_e32 v21, vcc, 0, v1, vcc
	v_add_co_u32_e32 v0, vcc, s28, v0
	global_load_dword v70, v[20:21], off offset:-4096
	s_nop 0
	global_load_dword v22, v[22:23], off
	v_addc_co_u32_e32 v1, vcc, 0, v1, vcc
	global_load_dword v23, v[0:1], off
	s_nop 0
	global_load_dword v20, v[20:21], off
	v_add_u32_e32 v0, s1, v4
	v_ashrrev_i32_e32 v1, 31, v0
	v_lshlrev_b64 v[0:1], 9, v[0:1]
	v_lshl_add_u64 v[0:1], s[52:53], 0, v[0:1]
	v_lshl_add_u64 v[66:67], v[0:1], 0, s[92:93]
	s_waitcnt vmcnt(62)
	v_cvt_pk_bf16_f32 v0, v3, v2
	s_waitcnt vmcnt(60)
	v_cvt_pk_bf16_f32 v1, v7, v6
	s_waitcnt vmcnt(58)
	v_cvt_pk_bf16_f32 v2, v9, v8
	s_waitcnt vmcnt(56)
	v_cvt_pk_bf16_f32 v3, v11, v10
	global_store_dwordx4 v[66:67], v[0:3], off sc1
	s_waitcnt vmcnt(55)
	s_nop 0
	v_cvt_pk_bf16_f32 v0, v13, v12
	s_waitcnt vmcnt(53)
	v_cvt_pk_bf16_f32 v1, v15, v14
	s_waitcnt vmcnt(51)
	v_cvt_pk_bf16_f32 v2, v17, v16
	s_waitcnt vmcnt(49)
	v_cvt_pk_bf16_f32 v3, v19, v18
	global_store_dwordx4 v[66:67], v[0:3], off offset:16 sc1
	s_waitcnt vmcnt(48)
	s_nop 0
	v_cvt_pk_bf16_f32 v0, v25, v24
	s_waitcnt vmcnt(46)
	v_cvt_pk_bf16_f32 v1, v27, v26
	s_waitcnt vmcnt(44)
	v_cvt_pk_bf16_f32 v2, v29, v28
	s_waitcnt vmcnt(42)
	v_cvt_pk_bf16_f32 v3, v31, v30
	global_store_dwordx4 v[66:67], v[0:3], off offset:32 sc1
	s_waitcnt vmcnt(41)
	s_nop 0
	v_cvt_pk_bf16_f32 v0, v33, v32
	s_waitcnt vmcnt(39)
	v_cvt_pk_bf16_f32 v1, v35, v34
	s_waitcnt vmcnt(37)
	v_cvt_pk_bf16_f32 v2, v37, v36
	s_waitcnt vmcnt(35)
	v_cvt_pk_bf16_f32 v3, v39, v38
	global_store_dwordx4 v[66:67], v[0:3], off offset:48 sc1
	s_waitcnt vmcnt(34)
	s_nop 0
	v_cvt_pk_bf16_f32 v0, v41, v40
	s_waitcnt vmcnt(32)
	v_cvt_pk_bf16_f32 v1, v43, v42
	s_waitcnt vmcnt(30)
	v_cvt_pk_bf16_f32 v2, v45, v44
	s_waitcnt vmcnt(28)
	v_cvt_pk_bf16_f32 v3, v47, v46
	global_store_dwordx4 v[66:67], v[0:3], off offset:64 sc1
	s_waitcnt vmcnt(27)
	s_nop 0
	v_cvt_pk_bf16_f32 v0, v49, v48
	s_waitcnt vmcnt(25)
	v_cvt_pk_bf16_f32 v1, v51, v50
	s_waitcnt vmcnt(23)
	v_cvt_pk_bf16_f32 v2, v53, v52
	s_waitcnt vmcnt(21)
	v_cvt_pk_bf16_f32 v3, v55, v54
	global_store_dwordx4 v[66:67], v[0:3], off offset:80 sc1
	s_waitcnt vmcnt(20)
	s_nop 0
	v_cvt_pk_bf16_f32 v0, v57, v56
	s_waitcnt vmcnt(18)
	v_cvt_pk_bf16_f32 v1, v59, v58
	s_waitcnt vmcnt(16)
	v_cvt_pk_bf16_f32 v2, v61, v60
	s_waitcnt vmcnt(14)
	v_cvt_pk_bf16_f32 v3, v63, v62
	global_store_dwordx4 v[66:67], v[0:3], off offset:96 sc1
	s_waitcnt vmcnt(13)
	s_nop 0
	v_cvt_pk_bf16_f32 v0, v65, v64
	s_waitcnt vmcnt(11)
	v_cvt_pk_bf16_f32 v1, v69, v68
	s_waitcnt vmcnt(9)
	v_cvt_pk_bf16_f32 v2, v22, v70
	s_waitcnt vmcnt(7)
	v_cvt_pk_bf16_f32 v3, v20, v23

.LBB0_812:
	s_andn2_b64 vcc, exec, s[0:1]
	s_cbranch_vccnz .LBB0_814
	s_and_b32 s0, s60, 0x3c0
	s_and_b32 s1, s12, 0x3c0
	s_lshl_b32 s28, s0, 12
	s_add_u32 s28, s39, s28
	s_addc_u32 s29, s40, 0
	s_lshl_b32 s30, s1, 2
	s_add_u32 s28, s28, s30
	s_addc_u32 s29, s29, 0
	v_lshl_add_u64 v[0:1], v[4:5], 2, s[28:29]
	v_add_co_u32_e32 v8, vcc, s11, v0
	s_movk_i32 s28, 0x4000
	s_nop 0
	v_addc_co_u32_e32 v9, vcc, 0, v1, vcc
	v_add_co_u32_e32 v10, vcc, s28, v0
	s_movk_i32 s28, 0x6000
	s_nop 0
	v_addc_co_u32_e32 v11, vcc, 0, v1, vcc
	v_add_co_u32_e32 v12, vcc, s28, v0
	s_mov_b32 s28, 0x8000
	s_nop 0
	v_addc_co_u32_e32 v13, vcc, 0, v1, vcc
	v_add_co_u32_e32 v14, vcc, s28, v0
	s_mov_b32 s28, 0xa000
	s_nop 0
	v_addc_co_u32_e32 v15, vcc, 0, v1, vcc
	s_waitcnt vmcnt(5)
	v_add_co_u32_e32 v16, vcc, s28, v0
	s_mov_b32 s28, 0xc000
	s_nop 0
	v_addc_co_u32_e32 v17, vcc, 0, v1, vcc
	v_add_co_u32_e32 v18, vcc, s28, v0
	s_mov_b32 s28, 0xe000
	s_nop 0
	v_addc_co_u32_e32 v19, vcc, 0, v1, vcc
	v_add_co_u32_e32 v20, vcc, s28, v0
	s_mov_b32 s28, 0x12000
	s_nop 0
	v_addc_co_u32_e32 v21, vcc, 0, v1, vcc
	v_add_co_u32_e32 v22, vcc, s67, v0
	global_load_dword v2, v[8:9], off offset:-4096
	global_load_dword v3, v[0:1], off
	v_addc_co_u32_e32 v23, vcc, 0, v1, vcc
	global_load_dword v6, v[10:11], off offset:-4096
	global_load_dword v7, v[8:9], off
	s_nop 0
	global_load_dword v8, v[12:13], off offset:-4096
	global_load_dword v9, v[10:11], off
	s_nop 0
	global_load_dword v10, v[14:15], off offset:-4096
	global_load_dword v11, v[12:13], off
	s_nop 0
	global_load_dword v12, v[16:17], off offset:-4096
	global_load_dword v13, v[14:15], off
	s_nop 0
	global_load_dword v14, v[18:19], off offset:-4096
	global_load_dword v15, v[16:17], off
	s_nop 0
	global_load_dword v16, v[20:21], off offset:-4096
	global_load_dword v17, v[18:19], off
	s_nop 0
	global_load_dword v18, v[22:23], off offset:-4096
	global_load_dword v19, v[20:21], off
	v_add_co_u32_e32 v20, vcc, s28, v0
	s_mov_b32 s28, 0x14000
	s_nop 0
	v_addc_co_u32_e32 v21, vcc, 0, v1, vcc
	global_load_dword v24, v[20:21], off offset:-4096
	global_load_dword v25, v[22:23], off
	v_add_co_u32_e32 v22, vcc, s28, v0
	s_mov_b32 s28, 0x16000
	s_nop 0
	v_addc_co_u32_e32 v23, vcc, 0, v1, vcc
	global_load_dword v26, v[22:23], off offset:-4096
	global_load_dword v27, v[20:21], off
	v_add_co_u32_e32 v20, vcc, s28, v0
	s_mov_b32 s28, 0x18000
	s_nop 0
	v_addc_co_u32_e32 v21, vcc, 0, v1, vcc
	global_load_dword v28, v[20:21], off offset:-4096
	global_load_dword v29, v[22:23], off
	v_add_co_u32_e32 v22, vcc, s28, v0
	s_mov_b32 s28, 0x1a000
	s_nop 0
	v_addc_co_u32_e32 v23, vcc, 0, v1, vcc
	global_load_dword v30, v[22:23], off offset:-4096
	global_load_dword v31, v[20:21], off
	v_add_co_u32_e32 v20, vcc, s28, v0
	s_mov_b32 s28, 0x1c000
	s_nop 0
	v_addc_co_u32_e32 v21, vcc, 0, v1, vcc
	global_load_dword v32, v[20:21], off offset:-4096
	global_load_dword v33, v[22:23], off
	v_add_co_u32_e32 v22, vcc, s28, v0
	s_mov_b32 s28, 0x1e000
	s_nop 0
	v_addc_co_u32_e32 v23, vcc, 0, v1, vcc
	global_load_dword v34, v[22:23], off offset:-4096
	global_load_dword v35, v[20:21], off
	v_add_co_u32_e32 v20, vcc, s28, v0
	s_mov_b32 s28, 0x20000
	s_nop 0
	v_addc_co_u32_e32 v21, vcc, 0, v1, vcc
	global_load_dword v36, v[20:21], off offset:-4096
	global_load_dword v37, v[22:23], off
	v_add_co_u32_e32 v22, vcc, s28, v0
	s_mov_b32 s28, 0x22000
	s_nop 0
	v_addc_co_u32_e32 v23, vcc, 0, v1, vcc
	global_load_dword v38, v[22:23], off offset:-4096
	global_load_dword v39, v[20:21], off
	v_add_co_u32_e32 v20, vcc, s28, v0
	s_mov_b32 s28, 0x24000
	s_nop 0
	v_addc_co_u32_e32 v21, vcc, 0, v1, vcc
	global_load_dword v40, v[20:21], off offset:-4096
	global_load_dword v41, v[22:23], off
	v_add_co_u32_e32 v22, vcc, s28, v0
	s_mov_b32 s28, 0x26000
	s_nop 0
	v_addc_co_u32_e32 v23, vcc, 0, v1, vcc
	global_load_dword v42, v[22:23], off offset:-4096
	global_load_dword v43, v[20:21], off
	v_add_co_u32_e32 v20, vcc, s28, v0
	s_mov_b32 s28, 0x2a000
	s_nop 0
	v_addc_co_u32_e32 v21, vcc, 0, v1, vcc
	global_load_dword v44, v[20:21], off offset:-4096
	global_load_dword v45, v[22:23], off
	v_add_co_u32_e32 v22, vcc, s95, v0
	s_lshl_b32 s92, s0, 1
	s_nop 0
	v_addc_co_u32_e32 v23, vcc, 0, v1, vcc
	global_load_dword v46, v[22:23], off offset:-4096
	global_load_dword v47, v[20:21], off
	v_add_co_u32_e32 v20, vcc, s28, v0
	s_mov_b32 s28, 0x2c000
	s_nop 0
	v_addc_co_u32_e32 v21, vcc, 0, v1, vcc
	global_load_dword v48, v[20:21], off offset:-4096
	global_load_dword v49, v[22:23], off
	v_add_co_u32_e32 v22, vcc, s28, v0
	s_mov_b32 s28, 0x2e000
	s_nop 0
	v_addc_co_u32_e32 v23, vcc, 0, v1, vcc
	global_load_dword v50, v[22:23], off offset:-4096
	global_load_dword v51, v[20:21], off
	v_add_co_u32_e32 v20, vcc, s28, v0
	s_mov_b32 s28, 0x30000
	s_nop 0
	v_addc_co_u32_e32 v21, vcc, 0, v1, vcc
	global_load_dword v52, v[20:21], off offset:-4096
	global_load_dword v53, v[22:23], off
	v_add_co_u32_e32 v22, vcc, s28, v0
	s_mov_b32 s28, 0x32000
	s_nop 0
	v_addc_co_u32_e32 v23, vcc, 0, v1, vcc
	global_load_dword v54, v[22:23], off offset:-4096
	global_load_dword v55, v[20:21], off
	v_add_co_u32_e32 v20, vcc, s28, v0
	s_mov_b32 s28, 0x34000
	s_nop 0
	v_addc_co_u32_e32 v21, vcc, 0, v1, vcc
	global_load_dword v56, v[20:21], off offset:-4096
	global_load_dword v57, v[22:23], off
	v_add_co_u32_e32 v22, vcc, s28, v0
	s_mov_b32 s28, 0x36000
	s_nop 0
	v_addc_co_u32_e32 v23, vcc, 0, v1, vcc
	global_load_dword v58, v[22:23], off offset:-4096
	global_load_dword v59, v[20:21], off
	v_add_co_u32_e32 v20, vcc, s28, v0
	s_mov_b32 s28, 0x38000
	s_nop 0
	v_addc_co_u32_e32 v21, vcc, 0, v1, vcc
	global_load_dword v60, v[20:21], off offset:-4096
	global_load_dword v61, v[22:23], off
	v_add_co_u32_e32 v22, vcc, s28, v0
	s_mov_b32 s28, 0x3a000
	s_nop 0
	v_addc_co_u32_e32 v23, vcc, 0, v1, vcc
	global_load_dword v62, v[22:23], off offset:-4096
	global_load_dword v63, v[20:21], off
	v_add_co_u32_e32 v20, vcc, s28, v0
	s_mov_b32 s28, 0x3c000
	s_nop 0
	v_addc_co_u32_e32 v21, vcc, 0, v1, vcc
	global_load_dword v64, v[20:21], off offset:-4096
	global_load_dword v65, v[22:23], off
	v_add_co_u32_e32 v22, vcc, s28, v0
	s_mov_b32 s28, 0x3e000
	s_nop 0
	v_addc_co_u32_e32 v23, vcc, 0, v1, vcc
	global_load_dword v68, v[22:23], off offset:-4096
	global_load_dword v69, v[20:21], off
	v_add_co_u32_e32 v20, vcc, s28, v0
	s_mov_b32 s28, 0x3f000
	s_nop 0
	v_addc_co_u32_e32 v21, vcc, 0, v1, vcc
	v_add_co_u32_e32 v0, vcc, s28, v0
	global_load_dword v70, v[20:21], off offset:-4096
	s_nop 0
	global_load_dword v22, v[22:23], off
	v_addc_co_u32_e32 v1, vcc, 0, v1, vcc
	global_load_dword v23, v[0:1], off
	s_nop 0
	global_load_dword v20, v[20:21], off
	v_add_u32_e32 v0, s1, v4
	v_ashrrev_i32_e32 v1, 31, v0
	v_lshlrev_b64 v[0:1], 9, v[0:1]
	v_lshl_add_u64 v[0:1], s[54:55], 0, v[0:1]
	v_lshl_add_u64 v[66:67], v[0:1], 0, s[92:93]
	s_waitcnt vmcnt(62)
	v_cvt_pk_bf16_f32 v0, v3, v2
	s_waitcnt vmcnt(60)
	v_cvt_pk_bf16_f32 v1, v7, v6
	s_waitcnt vmcnt(58)
	v_cvt_pk_bf16_f32 v2, v9, v8
	s_waitcnt vmcnt(56)
	v_cvt_pk_bf16_f32 v3, v11, v10
	global_store_dwordx4 v[66:67], v[0:3], off sc1
	s_waitcnt vmcnt(55)
	s_nop 0
	v_cvt_pk_bf16_f32 v0, v13, v12
	s_waitcnt vmcnt(53)
	v_cvt_pk_bf16_f32 v1, v15, v14
	s_waitcnt vmcnt(51)
	v_cvt_pk_bf16_f32 v2, v17, v16
	s_waitcnt vmcnt(49)
	v_cvt_pk_bf16_f32 v3, v19, v18
	global_store_dwordx4 v[66:67], v[0:3], off offset:16 sc1
	s_waitcnt vmcnt(48)
	s_nop 0
	v_cvt_pk_bf16_f32 v0, v25, v24
	s_waitcnt vmcnt(46)
	v_cvt_pk_bf16_f32 v1, v27, v26
	s_waitcnt vmcnt(44)
	v_cvt_pk_bf16_f32 v2, v29, v28
	s_waitcnt vmcnt(42)
	v_cvt_pk_bf16_f32 v3, v31, v30
	global_store_dwordx4 v[66:67], v[0:3], off offset:32 sc1
	s_waitcnt vmcnt(41)
	s_nop 0
	v_cvt_pk_bf16_f32 v0, v33, v32
	s_waitcnt vmcnt(39)
	v_cvt_pk_bf16_f32 v1, v35, v34
	s_waitcnt vmcnt(37)
	v_cvt_pk_bf16_f32 v2, v37, v36
	s_waitcnt vmcnt(35)
	v_cvt_pk_bf16_f32 v3, v39, v38
	global_store_dwordx4 v[66:67], v[0:3], off offset:48 sc1
	s_waitcnt vmcnt(34)
	s_nop 0
	v_cvt_pk_bf16_f32 v0, v41, v40
	s_waitcnt vmcnt(32)
	v_cvt_pk_bf16_f32 v1, v43, v42
	s_waitcnt vmcnt(30)
	v_cvt_pk_bf16_f32 v2, v45, v44
	s_waitcnt vmcnt(28)
	v_cvt_pk_bf16_f32 v3, v47, v46
	global_store_dwordx4 v[66:67], v[0:3], off offset:64 sc1
	s_waitcnt vmcnt(27)
	s_nop 0
	v_cvt_pk_bf16_f32 v0, v49, v48
	s_waitcnt vmcnt(25)
	v_cvt_pk_bf16_f32 v1, v51, v50
	s_waitcnt vmcnt(23)
	v_cvt_pk_bf16_f32 v2, v53, v52
	s_waitcnt vmcnt(21)
	v_cvt_pk_bf16_f32 v3, v55, v54
	global_store_dwordx4 v[66:67], v[0:3], off offset:80 sc1
	s_waitcnt vmcnt(20)
	s_nop 0
	v_cvt_pk_bf16_f32 v0, v57, v56
	s_waitcnt vmcnt(18)
	v_cvt_pk_bf16_f32 v1, v59, v58
	s_waitcnt vmcnt(16)
	v_cvt_pk_bf16_f32 v2, v61, v60
	s_waitcnt vmcnt(14)
	v_cvt_pk_bf16_f32 v3, v63, v62
	global_store_dwordx4 v[66:67], v[0:3], off offset:96 sc1
	s_waitcnt vmcnt(13)
	s_nop 0
	v_cvt_pk_bf16_f32 v0, v65, v64
	s_waitcnt vmcnt(11)
	v_cvt_pk_bf16_f32 v1, v69, v68
	s_waitcnt vmcnt(9)
	v_cvt_pk_bf16_f32 v2, v22, v70
	s_waitcnt vmcnt(7)
	v_cvt_pk_bf16_f32 v3, v20, v23

.LBB0_823:
	s_add_i32 s62, s62, s68
	s_add_i32 s12, s12, s20
	s_add_i32 s60, s60, s61
	s_cmpk_gt_i32 s62, 0xebf
	global_store_dwordx4 v[66:67], v[0:3], off offset:112 sc1
	s_cbranch_scc1 .LBB0_847
